# MLA row-sum MFMA: the ones operand only in rows 0,4,8,12 (3/4 zero multiplier inputs), same sums in register 0 of every lane
# baseline (speedup 1.0000x reference)
; template <bool MLA> __device__ __forceinline__ void attn_unit(const AttnP& P, int b, int hh, int qb, LAS char* lds) {
;     ...
;     const int qlo = q0 + wid * 32, qm = qlo + r32 - 4 * hi;
;     bf16x8 qr[NQF];
;     const size_t qrow = rowbase + qlo + r32;
;     if constexpr (MLA) {
; #pragma unroll
;         for (int d0 = 0; d0 < 8; ++d0) qr[d0] = *(const bf16x8*)(P.QN + qrow * 2048 + hh * 128 + d0 * 16 + hi * 8);
; #pragma unroll
;         for (int d0 = 0; d0 < 4; ++d0) qr[8 + d0] = *(const bf16x8*)(P.QR + qrow * 1024 + hh * 64 + d0 * 16 + hi * 8);
;     } else {
; #pragma unroll
;         for (int d0 = 0; d0 < 4; ++d0) qr[d0] = *(const bf16x8*)(P.QS + qrow * 2048 + hh * 64 + d0 * 16 + hi * 8);
;         if (tid < 128) bias_l[tid] = P.rel[(int)T5B[tid] * 32 + hh] * (1.0f / SCALE);
;     }
;     bf16x8 sk0, sv0;
;     const int sr8 = tid >> 3, ch8 = tid & 7;
;     const bf16_t* Kg; const bf16_t* Vg; const bf16_t* Rg = nullptr;
;     unsigned okA = 0, okB = 0, orp = 0, ovA = 0, ovB = 0;
;     if constexpr (MLA) {
;         Kg = P.KN + rowbase * 2048 + hh * 128; Vg = P.V + rowbase * 2048 + hh * 128; Rg = P.KR + rowbase * 64;
;         { const int rA = 4 * wid + (lane >> 4), rB = rA + 32, cp = lane & 15; okA = (unsigned)(rA * 2048 + ((cp ^ (rA & 7)) << 3)); okB = (unsigned)(rB * 2048 + ((cp ^ (rB & 7)) << 3)); }
;         { const int rr = 8 * wid + (lane >> 3), cp = lane & 7; orp = (unsigned)(rr * 64 + ((cp ^ (rr & 7)) << 3)); }
;         { const int stA = 2 * wid + (lane >> 5), stB = stA + 16; const int kl = (lane & 31) >> 2, c8 = 8 * (lane & 3);
;           const int kkA = (stA >> 2) * 8 + kl, kkB = (stB >> 2) * 8 + kl;
;           const int kA = (kkA & ~0xC) | ((kkA & 4) << 1) | ((kkA & 8) >> 1), kB = (kkB & ~0xC) | ((kkB & 4) << 1) | ((kkB & 8) >> 1);
;           ovA = (unsigned)(kA * 2048 + 32 * (stA & 3) + c8); ovB = (unsigned)(kB * 2048 + 32 * (stB & 3) + c8); }
;     } else { Kg = P.KS + (rowbase + sr8) * 256 + (hh >> 3) * 64 + ch8 * 8; Vg = P.VS + (rowbase + sr8) * 256 + (hh >> 3) * 64 + ch8 * 8; }
;     const int kws = KSWZ64(sr8, ch8), vst0 = v_st<NCB>(sr8, ch8 * 8);
;     ...
;     float m_reg = MLA ? 0.f : P.sinks[hh] * (1.0f / SCALE), l_reg = MLA ? 0.f : 1.f;
;     f32x16 o[NCB];
; #pragma unroll
;     for (int d = 0; d < NCB; ++d) o[d] = f32x16{};
;     const int vb0 = (int)(uintptr_t)V_lds + v_rd_base(lane);
.Lm16_qb_ok:
	s_lshr_b32 s36, s28, 5
	s_and_b32 s63, s36, 15
	s_lshr_b32 s64, s36, 4
	s_lshl_b32 s40, s33, 2
	s_add_u32 s40, s40, 4
	s_lshl_b32 s43, s33, 8
	s_lshl_b32 s36, s4, 5
	s_add_u32 s43, s43, s36
	s_lshl_b32 s36, s64, 14
	s_add_u32 s36, s36, s43
	s_lshl_b32 s37, s36, 12
	s_lshl_b32 s59, s63, 8
	s_add_u32 s37, s37, s59
	s_add_u32 s66, s6, s37
	s_addc_u32 s67, s7, 0
	s_lshl_b32 s37, s36, 11
	s_lshl_b32 s59, s63, 7
	s_add_u32 s37, s37, s59
	s_add_u32 s68, s8, s37
	s_addc_u32 s69, s9, 0
	s_lshl_b32 s37, s64, 26
	s_lshl_b32 s59, s63, 8
	s_add_u32 s37, s37, s59
	s_add_u32 s46, s12, s37
	s_addc_u32 s47, s13, 0
	s_add_u32 s48, s16, s37
	s_addc_u32 s49, s17, 0
	s_lshl_b32 s37, s64, 21
	s_add_u32 s50, s14, s37
	s_addc_u32 s51, s15, 0
	global_load_dwordx4 v[66:69], v237, s[66:67] offset:0
	global_load_dwordx4 v[70:73], v237, s[66:67] offset:64
	global_load_dwordx4 v[74:77], v237, s[66:67] offset:128
	global_load_dwordx4 v[78:81], v237, s[66:67] offset:192
	global_load_dwordx4 v[82:85], v239, s[68:69] offset:0
	global_load_dwordx4 v[86:89], v239, s[68:69] offset:64
	global_load_dwordx4 v[90:93], v238, s[66:67] offset:0
	global_load_dwordx4 v[94:97], v238, s[66:67] offset:64
	global_load_dwordx4 v[98:101], v238, s[66:67] offset:128
	global_load_dwordx4 v[102:105], v238, s[66:67] offset:192
	global_load_dwordx4 v[106:109], v240, s[68:69] offset:0
	global_load_dwordx4 v[110:113], v240, s[68:69] offset:64
	s_mov_b32 s70, 0x8000
	s_mov_b32 s71, 0
	s_add_i32 s36, s5, s70
	s_mov_b32 m0, s36
	s_nop 0
	global_load_lds_dwordx4 v232, s[46:47]
	s_add_i32 m0, s36, 0x2000
	s_nop 0
	global_load_lds_dwordx4 v233, s[46:47]
	s_add_i32 m0, s36, 0x4000
	s_nop 0
	global_load_lds_dwordx4 v234, s[50:51]
	s_add_i32 s36, s5, s71
	s_mov_b32 m0, s36
	s_nop 0
	global_load_lds_dwordx4 v235, s[48:49]
	s_add_i32 m0, s36, 0x2000
	s_nop 0
	global_load_lds_dwordx4 v236, s[48:49]
	s_add_u32 s46, s46, 0x40000
	s_addc_u32 s47, s47, 0
	s_add_u32 s48, s48, 0x40000
	s_addc_u32 s49, s49, 0
	s_add_u32 s50, s50, 0x2000
	s_addc_u32 s51, s51, 0
	v_mov_b32_e32 v2, 0
	v_mov_b32_e32 v3, 0
	v_mov_b32_e32 v4, 0
	v_mov_b32_e32 v5, 0
	v_mov_b32_e32 v6, 0
	v_mov_b32_e32 v7, 0
	v_mov_b32_e32 v8, 0
	v_mov_b32_e32 v9, 0
	v_mov_b32_e32 v10, 0
	v_mov_b32_e32 v11, 0
	v_mov_b32_e32 v12, 0
	v_mov_b32_e32 v13, 0
	v_mov_b32_e32 v14, 0
	v_mov_b32_e32 v15, 0
	v_mov_b32_e32 v16, 0
	v_mov_b32_e32 v17, 0
	v_mov_b32_e32 v18, 0
	v_mov_b32_e32 v19, 0
	v_mov_b32_e32 v20, 0
	v_mov_b32_e32 v21, 0
	v_mov_b32_e32 v22, 0
	v_mov_b32_e32 v23, 0
	v_mov_b32_e32 v24, 0
	v_mov_b32_e32 v25, 0
	v_mov_b32_e32 v26, 0
	v_mov_b32_e32 v27, 0
	v_mov_b32_e32 v28, 0
	v_mov_b32_e32 v29, 0
	v_mov_b32_e32 v30, 0
	v_mov_b32_e32 v31, 0
	v_mov_b32_e32 v32, 0
	v_mov_b32_e32 v33, 0
	v_mov_b32_e32 v34, 0
	v_mov_b32_e32 v35, 0
	v_mov_b32_e32 v36, 0
	v_mov_b32_e32 v37, 0
	v_mov_b32_e32 v38, 0
	v_mov_b32_e32 v39, 0
	v_mov_b32_e32 v40, 0
	v_mov_b32_e32 v41, 0
	v_mov_b32_e32 v42, 0
	v_mov_b32_e32 v43, 0
	v_mov_b32_e32 v44, 0
	v_mov_b32_e32 v45, 0
	v_mov_b32_e32 v46, 0
	v_mov_b32_e32 v47, 0
	v_mov_b32_e32 v48, 0
	v_mov_b32_e32 v49, 0
	v_mov_b32_e32 v50, 0
	v_mov_b32_e32 v51, 0
	v_mov_b32_e32 v52, 0
	v_mov_b32_e32 v53, 0
	v_mov_b32_e32 v54, 0
	v_mov_b32_e32 v55, 0
	v_mov_b32_e32 v56, 0
	v_mov_b32_e32 v57, 0
	v_mov_b32_e32 v58, 0
	v_mov_b32_e32 v59, 0
	v_mov_b32_e32 v60, 0
	v_mov_b32_e32 v61, 0
	v_mov_b32_e32 v62, 0
	v_mov_b32_e32 v63, 0
	v_mov_b32_e32 v64, 0
	v_mov_b32_e32 v65, 0
	v_mov_b32_e32 v218, 0
	v_mov_b32_e32 v146, 0
	v_mov_b32_e32 v147, 0
	v_mov_b32_e32 v148, 0
	v_mov_b32_e32 v149, 0
	v_and_b32_e32 v221, 3, v206
	v_cmp_eq_u32_e32 vcc, 0, v221
	v_mov_b32_e32 v222, 0x3f803f80
	s_nop 1
	v_cndmask_b32_e32 v154, 0, v222, vcc
	v_cndmask_b32_e32 v155, 0, v222, vcc
	v_cndmask_b32_e32 v156, 0, v222, vcc
	v_cndmask_b32_e32 v157, 0, v222, vcc
	v_mov_b32_e32 v208, 0xc0e00000
	v_mov_b32_e32 v209, 0xc0e00000
	v_mov_b32_e32 v210, 0xc0e00000
	v_mov_b32_e32 v211, 0xc0e00000
	v_mov_b32_e32 v219, 0
	v_mov_b32_e32 v150, 0
	v_mov_b32_e32 v151, 0
	v_mov_b32_e32 v152, 0
	v_mov_b32_e32 v153, 0
	v_mov_b32_e32 v212, 0xc0e00000
	v_mov_b32_e32 v213, 0xc0e00000
	v_mov_b32_e32 v214, 0xc0e00000
	v_mov_b32_e32 v215, 0xc0e00000
	s_mov_b32 s41, 0
	s_mov_b32 s42, 0
	s_waitcnt vmcnt(0)
	s_barrier
